# gdn_passB: 32 bf16 RNE bit-trick packs -> v_cvt_pk_bf16_f32
# speedup vs baseline: 1.0081x; 1.0021x over previous
.LBB0_726:
	v_cvt_pk_bf16_f32 v64, v32, v33
	v_cvt_pk_bf16_f32 v65, v34, v35
	v_cvt_pk_bf16_f32 v66, v56, v57
	v_cvt_pk_bf16_f32 v67, v58, v59
	v_cvt_pk_bf16_f32 v68, v60, v61
	v_cvt_pk_bf16_f32 v69, v62, v63
	v_cvt_pk_bf16_f32 v70, v36, v37
	v_cvt_pk_bf16_f32 v71, v38, v39
	v_cvt_pk_bf16_f32 v72, v40, v41
	v_cvt_pk_bf16_f32 v73, v42, v43
	v_cvt_pk_bf16_f32 v74, v48, v49
	v_cvt_pk_bf16_f32 v75, v50, v51
	v_cvt_pk_bf16_f32 v80, v52, v53
	v_cvt_pk_bf16_f32 v81, v54, v55
	v_cvt_pk_bf16_f32 v82, v44, v45
	v_add_u32_e32 v184, 0x8800, v172
	v_cvt_pk_bf16_f32 v83, v46, v47
	ds_write2_b64 v158, v[64:65], v[66:67] offset1:4
	ds_read2_b64 v[76:79], v184 offset0:128 offset1:132
	ds_write2_b64 v158, v[68:69], v[70:71] offset0:8 offset1:12
	ds_write2_b64 v158, v[72:73], v[74:75] offset0:16 offset1:20
	ds_write2_b64 v158, v[80:81], v[82:83] offset0:24 offset1:28
	v_add_u32_e32 v185, 0x8800, v164
	v_add_u32_e32 v186, 0x9800, v164
	v_add_u32_e32 v187, 0xa800, v164
	ds_read2_b64 v[84:87], v185 offset0:128 offset1:132
	ds_read2_b64 v[172:175], v186 offset0:160 offset1:164
	ds_read2_b64 v[176:179], v187 offset0:192 offset1:196
	s_waitcnt lgkmcnt(6)
	v_mfma_f32_16x16x32_bf16 v[76:79], v[76:79], v[64:67], 0
	ds_read2_b64 v[180:183], v184 offset0:136 offset1:140
	v_lshl_add_u64 v[100:101], v[100:101], 0, s[6:7]
	v_lshl_add_u64 v[102:103], v[102:103], 0, s[6:7]
	s_waitcnt lgkmcnt(3)
	v_mfma_f32_16x16x32_bf16 v[84:87], v[84:87], v[64:67], 0
	v_lshl_add_u64 v[104:105], v[104:105], 0, s[6:7]
	v_lshl_add_u64 v[106:107], v[106:107], 0, s[6:7]
	v_lshl_add_u64 v[108:109], v[108:109], 0, s[6:7]
	s_waitcnt lgkmcnt(2)
	v_mfma_f32_16x16x32_bf16 v[172:175], v[172:175], v[64:67], 0
	v_lshl_add_u64 v[110:111], v[110:111], 0, s[6:7]
	v_lshl_add_u64 v[112:113], v[112:113], 0, s[6:7]
	v_lshl_add_u64 v[114:115], v[114:115], 0, s[6:7]
	s_waitcnt lgkmcnt(1)
	v_mfma_f32_16x16x32_bf16 v[64:67], v[176:179], v[64:67], 0
	ds_read2_b64 v[176:179], v185 offset0:136 offset1:140
	v_lshl_add_u64 v[116:117], v[116:117], 0, s[6:7]
	s_cmp_lt_u32 s11, 30
	s_waitcnt lgkmcnt(1)
	v_mfma_f32_16x16x32_bf16 v[76:79], v[180:183], v[68:71], v[76:79]
	ds_read2_b64 v[180:183], v186 offset0:168 offset1:172
	s_mov_b32 s14, s11
	s_waitcnt lgkmcnt(1)
	v_mfma_f32_16x16x32_bf16 v[84:87], v[176:179], v[68:71], v[84:87]
	ds_read2_b64 v[176:179], v187 offset0:200 offset1:204
	s_waitcnt lgkmcnt(1)
	v_mfma_f32_16x16x32_bf16 v[172:175], v[180:183], v[68:71], v[172:175]
	ds_read2_b64 v[180:183], v184 offset0:144 offset1:148
	s_waitcnt lgkmcnt(1)
	v_mfma_f32_16x16x32_bf16 v[64:67], v[176:179], v[68:71], v[64:67]
	ds_read2_b64 v[68:71], v185 offset0:144 offset1:148
	ds_read2_b64 v[176:179], v186 offset0:176 offset1:180
	s_waitcnt lgkmcnt(1)
	v_mfma_f32_16x16x32_bf16 v[68:71], v[68:71], v[72:75], v[84:87]
	s_nop 2
	ds_read2_b64 v[84:87], v187 offset0:208 offset1:212
	s_waitcnt lgkmcnt(1)
	v_mfma_f32_16x16x32_bf16 v[172:175], v[176:179], v[72:75], v[172:175]
	ds_read2_b64 v[176:179], v184 offset0:152 offset1:156
	v_mfma_f32_16x16x32_bf16 v[76:79], v[180:183], v[72:75], v[76:79]
	s_waitcnt lgkmcnt(1)
	v_mfma_f32_16x16x32_bf16 v[84:87], v[84:87], v[72:75], v[64:67]
	ds_read2_b64 v[72:75], v186 offset0:184 offset1:188
	s_nop 1
	ds_read2_b64 v[64:67], v185 offset0:152 offset1:156
	ds_read2_b64 v[184:187], v187 offset0:216 offset1:220
	s_waitcnt lgkmcnt(3)
	v_mfma_f32_16x16x32_bf16 v[176:179], v[176:179], v[80:83], v[76:79]
	s_waitcnt lgkmcnt(1)
	v_mfma_f32_16x16x32_bf16 v[180:183], v[64:67], v[80:83], v[68:71]
	v_mfma_f32_16x16x32_bf16 v[172:175], v[72:75], v[80:83], v[172:175]
	ds_read_b128 v[76:79], v162
	ds_read_b128 v[64:67], v162 offset:2176
	ds_read_b128 v[72:75], v163
	ds_read_b128 v[68:71], v162 offset:3264
	s_waitcnt lgkmcnt(4)
	v_mfma_f32_16x16x32_bf16 v[184:187], v[184:187], v[80:83], v[84:87]
	v_lshlrev_b32_e32 v81, 16, v139
	v_lshlrev_b32_e32 v80, 16, v138
	v_mov_b32_e32 v82, v176
	v_mov_b32_e32 v83, v178
	v_pk_add_f32 v[80:81], v[80:81], v[82:83] neg_lo:[0,1] neg_hi:[0,1]
	v_and_b32_e32 v83, 0xffff0000, v139
	v_and_b32_e32 v82, 0xffff0000, v138
	v_mov_b32_e32 v178, v177
	v_pk_add_f32 v[82:83], v[82:83], v[178:179] neg_lo:[0,1] neg_hi:[0,1]
	v_and_b32_sdwa v84, v81, v165 dst_sel:DWORD dst_unused:UNUSED_PAD src0_sel:WORD_1 src1_sel:DWORD
	v_and_b32_sdwa v85, v80, v165 dst_sel:DWORD dst_unused:UNUSED_PAD src0_sel:WORD_1 src1_sel:DWORD
	v_add3_u32 v80, v80, v85, s2
	v_add3_u32 v81, v81, v84, s2
	v_and_b32_sdwa v84, v83, v165 dst_sel:DWORD dst_unused:UNUSED_PAD src0_sel:WORD_1 src1_sel:DWORD
	v_and_b32_sdwa v85, v82, v165 dst_sel:DWORD dst_unused:UNUSED_PAD src0_sel:WORD_1 src1_sel:DWORD
	v_add3_u32 v83, v83, v84, s2
	v_add3_u32 v82, v82, v85, s2
	v_and_b32_e32 v83, 0xffff0000, v83
	v_and_b32_e32 v82, 0xffff0000, v82
	v_or_b32_sdwa v85, v83, v81 dst_sel:DWORD dst_unused:UNUSED_PAD src0_sel:DWORD src1_sel:WORD_1
	v_or_b32_sdwa v84, v82, v80 dst_sel:DWORD dst_unused:UNUSED_PAD src0_sel:DWORD src1_sel:WORD_1
	v_lshlrev_b32_e32 v81, 16, v135
	v_lshlrev_b32_e32 v80, 16, v134
	v_mov_b32_e32 v82, v180
	v_mov_b32_e32 v83, v182
	v_pk_add_f32 v[80:81], v[80:81], v[82:83] neg_lo:[0,1] neg_hi:[0,1]
	v_and_b32_e32 v83, 0xffff0000, v135
	v_and_b32_e32 v82, 0xffff0000, v134
	v_mov_b32_e32 v182, v181
	v_pk_add_f32 v[82:83], v[82:83], v[182:183] neg_lo:[0,1] neg_hi:[0,1]
	v_and_b32_sdwa v86, v81, v165 dst_sel:DWORD dst_unused:UNUSED_PAD src0_sel:WORD_1 src1_sel:DWORD
	v_and_b32_sdwa v87, v80, v165 dst_sel:DWORD dst_unused:UNUSED_PAD src0_sel:WORD_1 src1_sel:DWORD
	v_add3_u32 v80, v80, v87, s2
	v_add3_u32 v81, v81, v86, s2
	v_and_b32_sdwa v86, v83, v165 dst_sel:DWORD dst_unused:UNUSED_PAD src0_sel:WORD_1 src1_sel:DWORD
	v_and_b32_sdwa v87, v82, v165 dst_sel:DWORD dst_unused:UNUSED_PAD src0_sel:WORD_1 src1_sel:DWORD
	v_add3_u32 v83, v83, v86, s2
	v_add3_u32 v82, v82, v87, s2
	v_and_b32_e32 v83, 0xffff0000, v83
	v_and_b32_e32 v82, 0xffff0000, v82
	v_or_b32_sdwa v87, v83, v81 dst_sel:DWORD dst_unused:UNUSED_PAD src0_sel:DWORD src1_sel:WORD_1
	v_or_b32_sdwa v86, v82, v80 dst_sel:DWORD dst_unused:UNUSED_PAD src0_sel:DWORD src1_sel:WORD_1
	v_lshlrev_b32_e32 v81, 16, v133
	v_lshlrev_b32_e32 v80, 16, v132
	v_mov_b32_e32 v82, v172
	v_mov_b32_e32 v83, v174
	v_pk_add_f32 v[80:81], v[80:81], v[82:83] neg_lo:[0,1] neg_hi:[0,1]
	v_and_b32_e32 v83, 0xffff0000, v133
	v_and_b32_e32 v82, 0xffff0000, v132
	v_mov_b32_e32 v174, v173
	v_pk_add_f32 v[82:83], v[82:83], v[174:175] neg_lo:[0,1] neg_hi:[0,1]
	v_and_b32_sdwa v132, v81, v165 dst_sel:DWORD dst_unused:UNUSED_PAD src0_sel:WORD_1 src1_sel:DWORD
	v_and_b32_sdwa v133, v80, v165 dst_sel:DWORD dst_unused:UNUSED_PAD src0_sel:WORD_1 src1_sel:DWORD
	v_add3_u32 v80, v80, v133, s2
	v_add3_u32 v81, v81, v132, s2
	v_and_b32_sdwa v132, v83, v165 dst_sel:DWORD dst_unused:UNUSED_PAD src0_sel:WORD_1 src1_sel:DWORD
	v_and_b32_sdwa v133, v82, v165 dst_sel:DWORD dst_unused:UNUSED_PAD src0_sel:WORD_1 src1_sel:DWORD
	v_add3_u32 v83, v83, v132, s2
	v_add3_u32 v82, v82, v133, s2
	v_and_b32_e32 v83, 0xffff0000, v83
	v_and_b32_e32 v82, 0xffff0000, v82
	v_or_b32_sdwa v81, v83, v81 dst_sel:DWORD dst_unused:UNUSED_PAD src0_sel:DWORD src1_sel:WORD_1
	v_or_b32_sdwa v80, v82, v80 dst_sel:DWORD dst_unused:UNUSED_PAD src0_sel:DWORD src1_sel:WORD_1
	v_lshlrev_b32_e32 v83, 16, v129
	v_lshlrev_b32_e32 v82, 16, v128
	v_mov_b32_e32 v132, v184
	v_mov_b32_e32 v133, v186
	v_pk_add_f32 v[82:83], v[82:83], v[132:133] neg_lo:[0,1] neg_hi:[0,1]
	v_and_b32_e32 v129, 0xffff0000, v129
	v_and_b32_e32 v128, 0xffff0000, v128
	v_mov_b32_e32 v186, v185
	v_pk_add_f32 v[128:129], v[128:129], v[186:187] neg_lo:[0,1] neg_hi:[0,1]
	v_and_b32_sdwa v132, v83, v165 dst_sel:DWORD dst_unused:UNUSED_PAD src0_sel:WORD_1 src1_sel:DWORD
	v_and_b32_sdwa v133, v82, v165 dst_sel:DWORD dst_unused:UNUSED_PAD src0_sel:WORD_1 src1_sel:DWORD
	v_add3_u32 v82, v82, v133, s2
	v_add3_u32 v83, v83, v132, s2
	v_and_b32_sdwa v132, v129, v165 dst_sel:DWORD dst_unused:UNUSED_PAD src0_sel:WORD_1 src1_sel:DWORD
	v_and_b32_sdwa v133, v128, v165 dst_sel:DWORD dst_unused:UNUSED_PAD src0_sel:WORD_1 src1_sel:DWORD
	v_add_u32_e32 v139, 0xd000, v171
	v_add3_u32 v129, v129, v132, s2
	v_add3_u32 v138, v128, v133, s2
	ds_read2_b64 v[132:135], v139 offset1:4
	ds_bpermute_b32 v128, v159, v89
	v_and_b32_e32 v129, 0xffff0000, v129
	v_and_b32_e32 v138, 0xffff0000, v138
	v_or_b32_sdwa v83, v129, v83 dst_sel:DWORD dst_unused:UNUSED_PAD src0_sel:DWORD src1_sel:WORD_1
	v_or_b32_sdwa v82, v138, v82 dst_sel:DWORD dst_unused:UNUSED_PAD src0_sel:DWORD src1_sel:WORD_1
	ds_write2_b64 v170, v[84:85], v[86:87] offset0:32 offset1:36
	ds_write2_b64 v170, v[80:81], v[82:83] offset0:40 offset1:44
	s_waitcnt lgkmcnt(2)
	v_pk_mul_f32 v[34:35], v[34:35], v[128:129] op_sel_hi:[1,0]
	v_pk_mul_f32 v[32:33], v[32:33], v[128:129] op_sel_hi:[1,0]
	v_add_u32_e32 v129, 0xd000, v169
	v_pk_mul_f32 v[58:59], v[58:59], v[128:129] op_sel_hi:[1,0]
	v_mfma_f32_16x16x32_bf16 v[32:35], v[132:135], v[84:87], v[32:35]
	ds_read2_b64 v[132:135], v129 offset1:4
	v_pk_mul_f32 v[56:57], v[56:57], v[128:129] op_sel_hi:[1,0]
	v_add_u32_e32 v138, 0xd800, v169
	v_pk_mul_f32 v[62:63], v[62:63], v[128:129] op_sel_hi:[1,0]
	s_waitcnt lgkmcnt(0)
	v_mfma_f32_16x16x32_bf16 v[56:59], v[132:135], v[84:87], v[56:59]
	ds_read2_b64 v[132:135], v138 offset0:32 offset1:36
	v_pk_mul_f32 v[60:61], v[60:61], v[128:129] op_sel_hi:[1,0]
	v_add_u32_e32 v178, 0xe000, v169
	v_pk_mul_f32 v[38:39], v[38:39], v[128:129] op_sel_hi:[1,0]
	s_waitcnt lgkmcnt(0)
	v_mfma_f32_16x16x32_bf16 v[132:135], v[132:135], v[84:87], v[60:63]
	s_nop 2
	ds_read2_b64 v[60:63], v178 offset0:64 offset1:68
	v_pk_mul_f32 v[36:37], v[36:37], v[128:129] op_sel_hi:[1,0]
	v_add_u32_e32 v179, 0xf000, v171
	v_pk_mul_f32 v[42:43], v[42:43], v[128:129] op_sel_hi:[1,0]
	s_waitcnt lgkmcnt(0)
	v_mfma_f32_16x16x32_bf16 v[36:39], v[60:63], v[84:87], v[36:39]
	ds_read2_b64 v[60:63], v179 offset0:128 offset1:132
	v_pk_mul_f32 v[40:41], v[40:41], v[128:129] op_sel_hi:[1,0]
	v_add_u32_e32 v180, 0xf800, v171
	v_pk_mul_f32 v[50:51], v[50:51], v[128:129] op_sel_hi:[1,0]
	s_waitcnt lgkmcnt(0)
	v_mfma_f32_16x16x32_bf16 v[40:43], v[60:63], v[84:87], v[40:43]
	ds_read2_b64 v[60:63], v180 offset0:160 offset1:164
	v_pk_mul_f32 v[48:49], v[48:49], v[128:129] op_sel_hi:[1,0]
	v_pk_mul_f32 v[54:55], v[54:55], v[128:129] op_sel_hi:[1,0]
	v_pk_mul_f32 v[52:53], v[52:53], v[128:129] op_sel_hi:[1,0]
	s_waitcnt lgkmcnt(0)
	v_mfma_f32_16x16x32_bf16 v[170:173], v[60:63], v[84:87], v[48:51]
	s_nop 2
	v_add_u32_e32 v48, 0x3000, v160
	ds_read2_b64 v[48:51], v48 offset0:192 offset1:196
	v_pk_mul_f32 v[46:47], v[46:47], v[128:129] op_sel_hi:[1,0]
	s_waitcnt lgkmcnt(0)
	v_mfma_f32_16x16x32_bf16 v[174:177], v[48:51], v[84:87], v[52:55]
	v_add_u32_e32 v48, 0x3800, v160
	ds_read2_b64 v[48:51], v48 offset0:224 offset1:228
	v_pk_mul_f32 v[44:45], v[44:45], v[128:129] op_sel_hi:[1,0]
	v_add_co_u32_e32 v128, vcc, s9, v148
	s_waitcnt lgkmcnt(0)
	v_mfma_f32_16x16x32_bf16 v[84:87], v[48:51], v[84:87], v[44:47]
	s_nop 2
	ds_read2_b64 v[44:47], v139 offset0:8 offset1:12
	v_add_u32_e32 v159, 8, v159
	s_waitcnt lgkmcnt(0)
	v_mfma_f32_16x16x32_bf16 v[32:35], v[44:47], v[80:83], v[32:35]
	ds_read2_b64 v[44:47], v129 offset0:8 offset1:12
	ds_read2_b64 v[48:51], v138 offset0:40 offset1:44
	v_addc_co_u32_e32 v129, vcc, 0, v149, vcc
	s_waitcnt lgkmcnt(1)
	v_mfma_f32_16x16x32_bf16 v[60:63], v[44:47], v[80:83], v[56:59]
	ds_read2_b64 v[44:47], v178 offset0:72 offset1:76
	v_add_co_u32_e32 v52, vcc, s9, v144
	s_waitcnt lgkmcnt(1)
	v_mfma_f32_16x16x32_bf16 v[56:59], v[48:51], v[80:83], v[132:135]
	ds_read2_b64 v[48:51], v179 offset0:136 offset1:140
	v_addc_co_u32_e32 v53, vcc, 0, v145, vcc
	global_store_dwordx4 v[128:129], v[76:79], off
	global_store_dwordx4 v[52:53], v[72:75], off
	global_store_dwordx4 v[128:129], v[64:67], off offset:2048
	global_store_dwordx4 v[128:129], v[68:71], off offset:3072
	s_waitcnt lgkmcnt(1)
	v_mfma_f32_16x16x32_bf16 v[52:55], v[44:47], v[80:83], v[36:39]
	s_nop 2
	ds_read2_b64 v[36:39], v180 offset0:168 offset1:172
	ds_read_b128 v[64:67], v167 offset:4352
	v_add_co_u32_e32 v72, vcc, s10, v142
	s_waitcnt lgkmcnt(2)
	v_mfma_f32_16x16x32_bf16 v[48:51], v[48:51], v[80:83], v[40:43]
	v_addc_co_u32_e32 v73, vcc, 0, v143, vcc
	s_waitcnt vmcnt(13)
	v_mov_b64_e32 v[138:139], v[118:119]
	v_add_u32_e32 v40, 0x3000, v161
	ds_read2_b64 v[40:43], v40 offset0:192 offset1:196
	s_waitcnt lgkmcnt(2)
	v_mfma_f32_16x16x32_bf16 v[44:47], v[36:39], v[80:83], v[170:173]
	v_add_u32_e32 v36, 0x3800, v161
	ds_read2_b64 v[36:39], v36 offset0:224 offset1:228
	ds_read_b128 v[68:71], v168 offset:4352
	s_waitcnt lgkmcnt(3)
	global_store_dwordx4 v[72:73], v[64:67], off
	s_waitcnt lgkmcnt(2)
	v_mfma_f32_16x16x32_bf16 v[40:43], v[40:43], v[80:83], v[174:177]
	v_add_co_u32_e32 v64, vcc, s10, v146
	s_waitcnt vmcnt(13)
	v_mov_b64_e32 v[134:135], v[120:121]
	v_addc_co_u32_e32 v65, vcc, 0, v147, vcc
	s_waitcnt lgkmcnt(0)
	global_store_dwordx4 v[64:65], v[68:71], off
	v_mfma_f32_16x16x32_bf16 v[36:39], v[36:39], v[80:83], v[84:87]
	s_waitcnt lgkmcnt(0)
	s_barrier
	s_waitcnt vmcnt(13)
	v_mov_b64_e32 v[132:133], v[122:123]
	s_waitcnt vmcnt(12)
	v_mov_b64_e32 v[128:129], v[124:125]
	s_cbranch_scc0 .LBB0_733

.LBB0_729:
	v_cvt_pk_bf16_f32 v64, v32, v33
	v_cvt_pk_bf16_f32 v65, v34, v35
	v_cvt_pk_bf16_f32 v66, v60, v61
	v_cvt_pk_bf16_f32 v67, v62, v63
	v_cvt_pk_bf16_f32 v68, v56, v57
	v_cvt_pk_bf16_f32 v69, v58, v59
	v_cvt_pk_bf16_f32 v70, v52, v53
	v_cvt_pk_bf16_f32 v71, v54, v55
	v_cvt_pk_bf16_f32 v72, v48, v49
	v_cvt_pk_bf16_f32 v73, v50, v51
	v_cvt_pk_bf16_f32 v74, v44, v45
	v_cvt_pk_bf16_f32 v75, v46, v47
	v_cvt_pk_bf16_f32 v80, v40, v41
	v_cvt_pk_bf16_f32 v81, v42, v43
	v_cvt_pk_bf16_f32 v82, v36, v37
	v_add_u32_e32 v172, v155, v154
	v_cvt_pk_bf16_f32 v83, v38, v39
	ds_read2_b64 v[76:79], v172 offset1:4
	ds_write2_b64 v158, v[64:65], v[66:67] offset1:4
	ds_write2_b64 v158, v[68:69], v[70:71] offset0:8 offset1:12
	ds_write2_b64 v158, v[72:73], v[74:75] offset0:16 offset1:20
	ds_write2_b64 v158, v[80:81], v[82:83] offset0:24 offset1:28
	v_add_u32_e32 v170, 0x1000, v164
	v_add_u32_e32 v171, 0x2000, v164
	ds_read2_b64 v[84:87], v164 offset1:4
	ds_read2_b64 v[142:145], v170 offset0:32 offset1:36
	ds_read2_b64 v[146:149], v171 offset0:64 offset1:68
	s_waitcnt lgkmcnt(7)
	v_mfma_f32_16x16x32_bf16 v[76:79], v[76:79], v[64:67], 0
	ds_read2_b64 v[174:177], v172 offset0:8 offset1:12
	ds_read2_b64 v[178:181], v171 offset0:88 offset1:92
	v_add_u32_e32 v173, -4, v159
	s_waitcnt lgkmcnt(4)
	v_mfma_f32_16x16x32_bf16 v[84:87], v[84:87], v[64:67], 0
	s_add_i32 s14, s14, 3
	s_cmp_gt_u32 s14, 30
	s_waitcnt lgkmcnt(3)
	v_mfma_f32_16x16x32_bf16 v[142:145], v[142:145], v[64:67], 0
	s_waitcnt lgkmcnt(2)
	v_mfma_f32_16x16x32_bf16 v[64:67], v[146:149], v[64:67], 0
	ds_read2_b64 v[146:149], v164 offset0:8 offset1:12
	s_waitcnt lgkmcnt(2)
	v_mfma_f32_16x16x32_bf16 v[76:79], v[174:177], v[68:71], v[76:79]
	ds_read2_b64 v[174:177], v170 offset0:40 offset1:44
	s_waitcnt lgkmcnt(1)
	v_mfma_f32_16x16x32_bf16 v[84:87], v[146:149], v[68:71], v[84:87]
	ds_read2_b64 v[146:149], v171 offset0:72 offset1:76
	s_waitcnt lgkmcnt(1)
	v_mfma_f32_16x16x32_bf16 v[142:145], v[174:177], v[68:71], v[142:145]
	ds_read2_b64 v[174:177], v172 offset0:16 offset1:20
	s_waitcnt lgkmcnt(1)
	v_mfma_f32_16x16x32_bf16 v[64:67], v[146:149], v[68:71], v[64:67]
	ds_read2_b64 v[68:71], v164 offset0:16 offset1:20
	ds_read2_b64 v[146:149], v170 offset0:48 offset1:52
	s_waitcnt lgkmcnt(1)
	v_mfma_f32_16x16x32_bf16 v[68:71], v[68:71], v[72:75], v[84:87]
	s_nop 2
	ds_read2_b64 v[84:87], v171 offset0:80 offset1:84
	v_add_u32_e32 v171, v155, v157
	v_add_u32_e32 v182, 0x7800, v171
	s_waitcnt lgkmcnt(1)
	v_mfma_f32_16x16x32_bf16 v[142:145], v[146:149], v[72:75], v[142:145]
	ds_read2_b64 v[146:149], v172 offset0:24 offset1:28
	v_add_u32_e32 v183, 0x8000, v171
	v_mfma_f32_16x16x32_bf16 v[76:79], v[174:177], v[72:75], v[76:79]
	s_waitcnt lgkmcnt(1)
	v_mfma_f32_16x16x32_bf16 v[84:87], v[84:87], v[72:75], v[64:67]
	ds_read2_b64 v[72:75], v170 offset0:56 offset1:60
	v_add_u32_e32 v170, 0x1000, v166
	s_nop 0
	ds_read2_b64 v[64:67], v164 offset0:24 offset1:28
	s_waitcnt lgkmcnt(2)
	v_mfma_f32_16x16x32_bf16 v[146:149], v[146:149], v[80:83], v[76:79]
	s_waitcnt lgkmcnt(0)
	v_mfma_f32_16x16x32_bf16 v[174:177], v[64:67], v[80:83], v[68:71]
	v_mfma_f32_16x16x32_bf16 v[142:145], v[72:75], v[80:83], v[142:145]
	ds_read_b128 v[76:79], v162
	ds_read_b128 v[64:67], v162 offset:2176
	ds_read_b128 v[72:75], v163
	ds_read_b128 v[68:71], v162 offset:3264
	v_mfma_f32_16x16x32_bf16 v[178:181], v[178:181], v[80:83], v[84:87]
	v_lshlrev_b32_e32 v81, 16, v141
	v_lshlrev_b32_e32 v80, 16, v140
	v_mov_b32_e32 v82, v146
	v_mov_b32_e32 v83, v148
	v_pk_add_f32 v[80:81], v[80:81], v[82:83] neg_lo:[0,1] neg_hi:[0,1]
	v_and_b32_e32 v83, 0xffff0000, v141
	v_and_b32_e32 v82, 0xffff0000, v140
	v_mov_b32_e32 v148, v147
	v_pk_add_f32 v[82:83], v[82:83], v[148:149] neg_lo:[0,1] neg_hi:[0,1]
	v_and_b32_sdwa v84, v81, v165 dst_sel:DWORD dst_unused:UNUSED_PAD src0_sel:WORD_1 src1_sel:DWORD
	v_and_b32_sdwa v85, v80, v165 dst_sel:DWORD dst_unused:UNUSED_PAD src0_sel:WORD_1 src1_sel:DWORD
	v_add3_u32 v80, v80, v85, s2
	v_add3_u32 v81, v81, v84, s2
	v_and_b32_sdwa v84, v83, v165 dst_sel:DWORD dst_unused:UNUSED_PAD src0_sel:WORD_1 src1_sel:DWORD
	v_and_b32_sdwa v85, v82, v165 dst_sel:DWORD dst_unused:UNUSED_PAD src0_sel:WORD_1 src1_sel:DWORD
	v_add3_u32 v83, v83, v84, s2
	v_add3_u32 v82, v82, v85, s2
	v_and_b32_e32 v83, 0xffff0000, v83
	v_and_b32_e32 v82, 0xffff0000, v82
	v_or_b32_sdwa v85, v83, v81 dst_sel:DWORD dst_unused:UNUSED_PAD src0_sel:DWORD src1_sel:WORD_1
	v_or_b32_sdwa v84, v82, v80 dst_sel:DWORD dst_unused:UNUSED_PAD src0_sel:DWORD src1_sel:WORD_1
	v_lshlrev_b32_e32 v81, 16, v137
	v_lshlrev_b32_e32 v80, 16, v136
	v_mov_b32_e32 v82, v174
	v_mov_b32_e32 v83, v176
	v_pk_add_f32 v[80:81], v[80:81], v[82:83] neg_lo:[0,1] neg_hi:[0,1]
	v_and_b32_e32 v83, 0xffff0000, v137
	v_and_b32_e32 v82, 0xffff0000, v136
	v_mov_b32_e32 v176, v175
	v_pk_add_f32 v[82:83], v[82:83], v[176:177] neg_lo:[0,1] neg_hi:[0,1]
	v_and_b32_sdwa v86, v81, v165 dst_sel:DWORD dst_unused:UNUSED_PAD src0_sel:WORD_1 src1_sel:DWORD
	v_and_b32_sdwa v87, v80, v165 dst_sel:DWORD dst_unused:UNUSED_PAD src0_sel:WORD_1 src1_sel:DWORD
	v_add3_u32 v80, v80, v87, s2
	v_add3_u32 v81, v81, v86, s2
	v_and_b32_sdwa v86, v83, v165 dst_sel:DWORD dst_unused:UNUSED_PAD src0_sel:WORD_1 src1_sel:DWORD
	v_and_b32_sdwa v87, v82, v165 dst_sel:DWORD dst_unused:UNUSED_PAD src0_sel:WORD_1 src1_sel:DWORD
	v_add3_u32 v83, v83, v86, s2
	v_add3_u32 v82, v82, v87, s2
	v_and_b32_e32 v83, 0xffff0000, v83
	v_and_b32_e32 v82, 0xffff0000, v82
	v_or_b32_sdwa v87, v83, v81 dst_sel:DWORD dst_unused:UNUSED_PAD src0_sel:DWORD src1_sel:WORD_1
	v_or_b32_sdwa v86, v82, v80 dst_sel:DWORD dst_unused:UNUSED_PAD src0_sel:DWORD src1_sel:WORD_1
	v_lshlrev_b32_e32 v81, 16, v131
	v_lshlrev_b32_e32 v80, 16, v130
	v_mov_b32_e32 v82, v142
	v_mov_b32_e32 v83, v144
	v_pk_add_f32 v[80:81], v[80:81], v[82:83] neg_lo:[0,1] neg_hi:[0,1]
	v_and_b32_e32 v83, 0xffff0000, v131
	v_and_b32_e32 v82, 0xffff0000, v130
	v_mov_b32_e32 v144, v143
	v_pk_add_f32 v[82:83], v[82:83], v[144:145] neg_lo:[0,1] neg_hi:[0,1]
	v_and_b32_sdwa v130, v81, v165 dst_sel:DWORD dst_unused:UNUSED_PAD src0_sel:WORD_1 src1_sel:DWORD
	v_and_b32_sdwa v131, v80, v165 dst_sel:DWORD dst_unused:UNUSED_PAD src0_sel:WORD_1 src1_sel:DWORD
	v_add3_u32 v80, v80, v131, s2
	v_add3_u32 v81, v81, v130, s2
	v_and_b32_sdwa v130, v83, v165 dst_sel:DWORD dst_unused:UNUSED_PAD src0_sel:WORD_1 src1_sel:DWORD
	v_and_b32_sdwa v131, v82, v165 dst_sel:DWORD dst_unused:UNUSED_PAD src0_sel:WORD_1 src1_sel:DWORD
	v_add3_u32 v83, v83, v130, s2
	v_add3_u32 v82, v82, v131, s2
	v_and_b32_e32 v83, 0xffff0000, v83
	v_and_b32_e32 v82, 0xffff0000, v82
	v_or_b32_sdwa v81, v83, v81 dst_sel:DWORD dst_unused:UNUSED_PAD src0_sel:DWORD src1_sel:WORD_1
	v_or_b32_sdwa v80, v82, v80 dst_sel:DWORD dst_unused:UNUSED_PAD src0_sel:DWORD src1_sel:WORD_1
	v_lshlrev_b32_e32 v83, 16, v127
	v_lshlrev_b32_e32 v82, 16, v126
	v_mov_b32_e32 v130, v178
	v_mov_b32_e32 v131, v180
	v_pk_add_f32 v[82:83], v[82:83], v[130:131] neg_lo:[0,1] neg_hi:[0,1]
	v_and_b32_e32 v127, 0xffff0000, v127
	v_and_b32_e32 v126, 0xffff0000, v126
	v_mov_b32_e32 v180, v179
	v_pk_add_f32 v[126:127], v[126:127], v[180:181] neg_lo:[0,1] neg_hi:[0,1]
	v_and_b32_sdwa v131, v82, v165 dst_sel:DWORD dst_unused:UNUSED_PAD src0_sel:WORD_1 src1_sel:DWORD
	v_and_b32_sdwa v130, v83, v165 dst_sel:DWORD dst_unused:UNUSED_PAD src0_sel:WORD_1 src1_sel:DWORD
	v_add3_u32 v82, v82, v131, s2
	v_and_b32_sdwa v131, v126, v165 dst_sel:DWORD dst_unused:UNUSED_PAD src0_sel:WORD_1 src1_sel:DWORD
	v_add3_u32 v83, v83, v130, s2
	v_and_b32_sdwa v130, v127, v165 dst_sel:DWORD dst_unused:UNUSED_PAD src0_sel:WORD_1 src1_sel:DWORD
	v_add3_u32 v126, v126, v131, s2
	v_add_u32_e32 v131, 0x4000, v171
	v_add3_u32 v127, v127, v130, s2
	ds_read2_b64 v[140:143], v131 offset0:128 offset1:132
	v_and_b32_e32 v127, 0xffff0000, v127
	v_and_b32_e32 v130, 0xffff0000, v126
	v_or_b32_sdwa v83, v127, v83 dst_sel:DWORD dst_unused:UNUSED_PAD src0_sel:DWORD src1_sel:WORD_1
	v_or_b32_sdwa v82, v130, v82 dst_sel:DWORD dst_unused:UNUSED_PAD src0_sel:DWORD src1_sel:WORD_1
	ds_write2_b64 v170, v[84:85], v[86:87] offset0:32 offset1:36
	ds_bpermute_b32 v126, v173, v89
	ds_write2_b64 v170, v[80:81], v[82:83] offset0:40 offset1:44
	v_add_u32_e32 v127, 0x4000, v169
	ds_read2_b64 v[144:147], v127 offset0:128 offset1:132
	v_add_u32_e32 v130, 0x4800, v169
	s_waitcnt lgkmcnt(2)
	v_pk_mul_f32 v[34:35], v[34:35], v[126:127] op_sel_hi:[1,0]
	v_pk_mul_f32 v[32:33], v[32:33], v[126:127] op_sel_hi:[1,0]
	v_pk_mul_f32 v[62:63], v[62:63], v[126:127] op_sel_hi:[1,0]
	v_pk_mul_f32 v[60:61], v[60:61], v[126:127] op_sel_hi:[1,0]
	v_mfma_f32_16x16x32_bf16 v[32:35], v[140:143], v[84:87], v[32:35]
	ds_read2_b64 v[140:143], v130 offset0:160 offset1:164
	v_add_u32_e32 v136, 0x5000, v169
	v_pk_mul_f32 v[58:59], v[58:59], v[126:127] op_sel_hi:[1,0]
	s_waitcnt lgkmcnt(1)
	v_mfma_f32_16x16x32_bf16 v[60:63], v[144:147], v[84:87], v[60:63]
	ds_read2_b64 v[144:147], v136 offset0:192 offset1:196
	v_pk_mul_f32 v[56:57], v[56:57], v[126:127] op_sel_hi:[1,0]
	v_add_u32_e32 v137, 0x6800, v171
	v_pk_mul_f32 v[54:55], v[54:55], v[126:127] op_sel_hi:[1,0]
	s_waitcnt lgkmcnt(1)
	v_mfma_f32_16x16x32_bf16 v[140:143], v[140:143], v[84:87], v[56:59]
	v_mul_f32_e64 v52, v52, v126
	v_mul_f32_e64 v53, v53, v126
	v_add_u32_e32 v173, 0x7000, v171
	ds_read2_b64 v[56:59], v137 offset1:4
	s_waitcnt lgkmcnt(1)
	v_mfma_f32_16x16x32_bf16 v[52:55], v[144:147], v[84:87], v[52:55]
	ds_read2_b64 v[144:147], v173 offset0:32 offset1:36
	v_pk_mul_f32 v[50:51], v[50:51], v[126:127] op_sel_hi:[1,0]
	v_pk_mul_f32 v[48:49], v[48:49], v[126:127] op_sel_hi:[1,0]
	v_pk_mul_f32 v[46:47], v[46:47], v[126:127] op_sel_hi:[1,0]
	v_pk_mul_f32 v[44:45], v[44:45], v[126:127] op_sel_hi:[1,0]
	s_waitcnt lgkmcnt(1)
	v_mfma_f32_16x16x32_bf16 v[48:51], v[56:59], v[84:87], v[48:51]
	ds_read2_b64 v[56:59], v182 offset0:64 offset1:68
	v_pk_mul_f32 v[42:43], v[42:43], v[126:127] op_sel_hi:[1,0]
	v_pk_mul_f32 v[40:41], v[40:41], v[126:127] op_sel_hi:[1,0]
	s_waitcnt lgkmcnt(1)
	v_mfma_f32_16x16x32_bf16 v[44:47], v[144:147], v[84:87], v[44:47]
	ds_read2_b64 v[144:147], v183 offset0:96 offset1:100
	v_pk_mul_f32 v[38:39], v[38:39], v[126:127] op_sel_hi:[1,0]
	v_pk_mul_f32 v[36:37], v[36:37], v[126:127] op_sel_hi:[1,0]
	s_waitcnt lgkmcnt(1)
	v_mfma_f32_16x16x32_bf16 v[174:177], v[56:59], v[84:87], v[40:43]
	ds_read2_b64 v[178:181], v136 offset0:200 offset1:204
	s_nop 1
	ds_read2_b64 v[40:43], v131 offset0:136 offset1:140
	v_lshl_add_u64 v[148:149], v[100:101], 0, s[4:5]
	s_waitcnt lgkmcnt(2)
	v_mfma_f32_16x16x32_bf16 v[84:87], v[144:147], v[84:87], v[36:39]
	global_store_dwordx4 v[148:149], v[76:79], off
	ds_read2_b64 v[76:79], v137 offset0:8 offset1:12
	v_lshl_add_u64 v[144:145], v[102:103], 0, s[4:5]
	ds_read2_b64 v[36:39], v127 offset0:136 offset1:140
	s_waitcnt lgkmcnt(2)
	v_mfma_f32_16x16x32_bf16 v[32:35], v[40:43], v[80:83], v[32:35]
	ds_read2_b64 v[40:43], v130 offset0:168 offset1:172
	global_store_dwordx4 v[144:145], v[72:75], off
	global_store_dwordx4 v[148:149], v[64:67], off offset:2048
	global_store_dwordx4 v[148:149], v[68:71], off offset:3072
	v_lshl_add_u64 v[146:147], v[116:117], 0, s[4:5]
	s_waitcnt lgkmcnt(1)
	v_mfma_f32_16x16x32_bf16 v[56:59], v[36:39], v[80:83], v[60:63]
	v_mfma_f32_16x16x32_bf16 v[36:39], v[178:181], v[80:83], v[52:55]
	s_nop 2
	ds_read_b128 v[52:55], v167 offset:4352
	ds_read2_b64 v[64:67], v173 offset0:40 offset1:44
	ds_read2_b64 v[68:71], v182 offset0:72 offset1:76
	ds_read_b128 v[72:75], v168 offset:4352
	s_waitcnt lgkmcnt(4)
	v_mfma_f32_16x16x32_bf16 v[60:63], v[40:43], v[80:83], v[140:143]
	v_mfma_f32_16x16x32_bf16 v[40:43], v[76:79], v[80:83], v[48:51]
	s_nop 1
	v_lshl_add_u64 v[142:143], v[104:105], 0, s[4:5]
	v_add_co_u32_e32 v76, vcc, s8, v142
	s_waitcnt lgkmcnt(2)
	v_mfma_f32_16x16x32_bf16 v[48:51], v[64:67], v[80:83], v[44:47]
	v_addc_co_u32_e32 v77, vcc, 0, v143, vcc
	v_add_co_u32_e32 v64, vcc, s8, v146
	s_nop 0
	ds_read2_b64 v[44:47], v183 offset0:104 offset1:108
	v_addc_co_u32_e32 v65, vcc, 0, v147, vcc
	global_store_dwordx4 v[76:77], v[52:55], off
	s_waitcnt lgkmcnt(1)
	global_store_dwordx4 v[64:65], v[72:75], off
	s_waitcnt lgkmcnt(0)
	v_mfma_f32_16x16x32_bf16 v[44:47], v[44:47], v[80:83], v[84:87]
	s_waitcnt lgkmcnt(0)
	s_barrier
	v_mfma_f32_16x16x32_bf16 v[52:55], v[68:71], v[80:83], v[174:177]
	s_cbranch_scc1 .LBB0_732
	s_cmp_gt_u32 s14, 28
	s_waitcnt vmcnt(6)
	v_mov_b64_e32 v[64:65], v[98:99]
	v_mov_b64_e32 v[66:67], v[96:97]
	v_mov_b64_e32 v[68:69], v[94:95]
	v_mov_b64_e32 v[70:71], v[92:93]
	ds_write_b128 v150, v[16:19]
	ds_write_b128 v151, v[20:23]
	ds_write_b128 v152, v[24:27] offset:17408
	ds_write_b128 v153, v[28:31] offset:17408
	s_cbranch_scc1 .LBB0_725
	v_lshl_add_u64 v[16:17], v[114:115], 0, s[4:5]
	v_add_co_u32_e32 v16, vcc, 0x3010000, v16
	v_lshl_add_u64 v[20:21], v[112:113], 0, s[4:5]
	s_nop 0
	v_addc_co_u32_e32 v17, vcc, 0, v17, vcc
	v_add_co_u32_e32 v20, vcc, 0x3010000, v20
	v_lshl_add_u64 v[24:25], v[110:111], 0, s[4:5]
	s_nop 0
	v_addc_co_u32_e32 v21, vcc, 0, v21, vcc
	v_add_co_u32_e32 v24, vcc, 0x117c0000, v24
	v_lshl_add_u64 v[28:29], v[108:109], 0, s[4:5]
	s_nop 0
	v_addc_co_u32_e32 v25, vcc, 0, v25, vcc
	v_add_co_u32_e32 v28, vcc, 0x117c0000, v28
	v_lshl_add_u64 v[64:65], v[106:107], 0, s[4:5]
	s_nop 0
	v_addc_co_u32_e32 v29, vcc, 0, v29, vcc
	v_add_co_u32_e32 v64, vcc, 0x2010000, v64
	global_load_dwordx4 v[16:19], v[16:17], off
	s_nop 0
	v_addc_co_u32_e32 v65, vcc, 0, v65, vcc
	global_load_dwordx4 v[20:23], v[20:21], off
	s_nop 0
	global_load_dwordx4 v[24:27], v[24:25], off
	s_nop 0
	global_load_dwordx4 v[28:31], v[28:29], off
	s_nop 0
	global_load_dwordx2 v[70:71], v[64:65], off
	global_load_dwordx2 v[68:69], v[64:65], off offset:32
	global_load_dwordx2 v[66:67], v[64:65], off offset:64
	s_nop 0
	global_load_dwordx2 v[64:65], v[64:65], off offset:96
	s_branch .LBB0_725
